# grid.sync after P0 replaced by hand-written XCD-hierarchical barrier (same protocol as the other barriers, census loads in one wave instruction); P7: conv_fixup -> GEMM hand-off keeps vmcnt(0)+s_barri
# speedup vs baseline: 1.0430x; 1.0430x over previous
; __device__ __forceinline__ int lane_id_() { int l; asm volatile("v_mbcnt_lo_u32_b32 %0, -1, 0\n\tv_mbcnt_hi_u32_b32 %0, -1, %0" : "=v"(l)); return l; }
; __device__ __forceinline__ void xcd_barrier_complete(unsigned* bar, unsigned x, unsigned& nloc, unsigned& nx) {
;     const unsigned G = gridDim.x;
;     unsigned sum, cnt, mine, sp = 0u;
;     for (;;) {
;         sum = 0u; cnt = 0u; mine = 0u;
; #pragma unroll
;         for (unsigned j = 0; j < 16; ++j) { const unsigned c = xb_ld(&bar[XB_XCNT(j)]); sum += c; cnt += (c > 0u) ? 1u : 0u; mine = (j == x) ? c : mine; }
;         if (sum == G) break;
;         __builtin_amdgcn_s_sleep(1);
;         if ((++sp & 255u) == 0u) { if (xb_ld(&bar[XB_TMO])) break; if (sp > XB_SPIN_CAP) { atomicAdd(&bar[XB_TMO], 1u); break; } }
;     }
;     nloc = mine > 0u ? mine : 1u; nx = cnt > 0u ? cnt : 1u;
; }
; __device__ __forceinline__ void xcd_barrier(const XcdBarrier& b, const int WID) {
;     asm volatile("s_waitcnt vmcnt(0)" ::: "memory");
;     __syncthreads();
;     if (WID == 0 && lane_id_() == 0) {
;         unsigned* bar = b.bar;
;         __builtin_amdgcn_s_waitcnt(0);
;         unsigned nloc = b.st[0], nx = b.st[1];
;         if (nloc == 0u) { xcd_barrier_complete(bar, b.x, nloc, nx); b.st[0] = nloc; b.st[1] = nx; }
;         const unsigned old = xb_add(&bar[XB_XSUB(b.x)], 1u);
;         const unsigned gen = old / nloc;
;         if (old + 1u == (gen + 1u) * nloc) {
;             __builtin_amdgcn_fence(__ATOMIC_RELEASE, "agent");
;             asm volatile("s_waitcnt vmcnt(0)" ::: "memory");
;             const unsigned og = xb_add(&bar[XB_TOP], 1u);
;             const unsigned tg = og / nx;
;             if (og + 1u == (tg + 1u) * nx) xb_add(&bar[XB_TOPGEN], 1u);
;             else XB_SPIN(xb_ld(&bar[XB_TOPGEN]) == tg, bar);
;             __builtin_amdgcn_fence(__ATOMIC_ACQUIRE, "agent");
;             xb_add(&bar[XB_XGEN(b.x)], 1u);
;             asm volatile("s_waitcnt vmcnt(0)" ::: "memory");
;         } else {
;             XB_SPIN(xb_ld(&bar[XB_XGEN(b.x)]) == gen, bar);
;             __builtin_amdgcn_fence(__ATOMIC_ACQUIRE, "agent");
;             asm volatile("s_waitcnt vmcnt(0)" ::: "memory");
;         }
; __global__ void __launch_bounds__(512) mega(Params p) {
;     ...
;     grid.sync();
.LBB0_63:
	s_waitcnt vmcnt(0)
	v_lshrrev_b32_e32 v2, 20, v0
	v_lshrrev_b32_e32 v0, 10, v0
	v_or_b32_e32 v0, v0, v2
	s_movk_i32 s0, 0x3ff
	v_and_or_b32 v0, v0, s0, v1
	v_cmp_eq_u32_e32 vcc, 0, v0
	s_barrier
	s_barrier
	s_and_saveexec_b64 s[0:1], vcc
	s_xor_b64 s[0:1], exec, s[0:1]
	v_readlane_b32 s81, v254, 0
	s_cbranch_execz .LBB0_73
	s_add_u32 s4, s94, 0x1de00000
	s_addc_u32 s5, s95, 0
	s_mov_b64 exec, 0xffff
	v_mbcnt_lo_u32_b32 v2, -1, 0
	v_lshlrev_b32_e32 v2, 8, v2
	s_mov_b32 s98, 0
.Lgb_census:
	global_load_dword v1, v2, s[4:5] offset:1024 sc1
	s_waitcnt vmcnt(0)
	v_cmp_ne_u32_e32 vcc, 0, v1
	v_readlane_b32 s9, v1, 0
	v_readlane_b32 s10, v1, 1
	v_readlane_b32 s11, v1, 2
	v_readlane_b32 s99, v1, 3
	s_add_u32 s9, s9, s10
	s_add_u32 s11, s11, s99
	v_readlane_b32 s10, v1, 4
	v_readlane_b32 s99, v1, 5
	s_add_u32 s9, s9, s11
	s_add_u32 s10, s10, s99
	v_readlane_b32 s11, v1, 6
	v_readlane_b32 s99, v1, 7
	s_add_u32 s9, s9, s10
	s_add_u32 s11, s11, s99
	v_readlane_b32 s10, v1, 8
	v_readlane_b32 s99, v1, 9
	s_add_u32 s9, s9, s11
	s_add_u32 s10, s10, s99
	v_readlane_b32 s11, v1, 10
	v_readlane_b32 s99, v1, 11
	s_add_u32 s9, s9, s10
	s_add_u32 s11, s11, s99
	v_readlane_b32 s10, v1, 12
	v_readlane_b32 s99, v1, 13
	s_add_u32 s9, s9, s11
	s_add_u32 s10, s10, s99
	v_readlane_b32 s11, v1, 14
	v_readlane_b32 s99, v1, 15
	s_add_u32 s9, s9, s10
	s_add_u32 s11, s11, s99
	s_add_u32 s9, s9, s11
	v_readlane_b32 s7, v1, s3
	s_and_b64 s[10:11], vcc, exec
	s_bcnt1_i32_b64 s8, s[10:11]
	s_cmp_eq_u32 s9, s96
	s_cbranch_scc1 .Lgb_census_done
	s_sleep 1
	s_add_u32 s98, s98, 1
	s_cmp_lt_u32 s98, 0x10000
	s_cbranch_scc1 .Lgb_census
.Lgb_census_done:
	s_max_u32 s7, s7, 1
	s_max_u32 s8, s8, 1
	s_mov_b64 exec, 1
	v_mov_b32_e32 v2, 0x253f0
	v_mov_b32_e32 v3, s7
	ds_write_b32 v2, v3
	v_mov_b32_e32 v3, s8
	ds_write_b32 v2, v3 offset:4
	s_lshl_b32 s6, s3, 8
	s_add_u32 s9, s6, 0x1400
	v_mov_b32_e32 v2, s9
	v_mov_b32_e32 v3, 1
	global_atomic_add v1, v2, v3, s[4:5] sc0
	s_waitcnt vmcnt(0)
	v_readfirstlane_b32 s10, v1
	s_add_u32 s10, s10, 1
	s_add_u32 s9, s6, 0x2400
	s_cmp_lg_u32 s10, s7
	s_cbranch_scc1 .Lgb_follower
	buffer_wbl2 sc1
	s_waitcnt vmcnt(0) lgkmcnt(0)
	v_mov_b32_e32 v2, 0x3400
	global_atomic_add v1, v2, v3, s[4:5] sc0
	s_waitcnt vmcnt(0)
	v_readfirstlane_b32 s10, v1
	s_add_u32 s10, s10, 1
	v_mov_b32_e32 v2, 0x3500
	s_cmp_lg_u32 s10, s8
	s_cbranch_scc1 .Lgb_topwait
	global_atomic_add v2, v3, s[4:5]
	s_branch .Lgb_topdone
.Lgb_topwait:
	s_mov_b32 s98, 0
.Lgb_topspin:
	global_load_dword v1, v2, s[4:5] sc1
	s_waitcnt vmcnt(0)
	v_readfirstlane_b32 s10, v1
	s_cmp_lg_u32 s10, 0
	s_cbranch_scc1 .Lgb_topdone
	s_sleep 1
	s_add_u32 s98, s98, 1
	s_cmp_lt_u32 s98, 0x10000
	s_cbranch_scc1 .Lgb_topspin
.Lgb_topdone:
	s_waitcnt vmcnt(0)
	buffer_inv sc1
	v_mov_b32_e32 v2, s9
	s_nop 0
	global_atomic_add v2, v3, s[4:5]
	s_waitcnt vmcnt(0)
	s_branch .Lgb_done
.Lgb_follower:
	v_mov_b32_e32 v2, s9
	s_mov_b32 s98, 0

; __device__ __forceinline__ int lane_id_() { int l; asm volatile("v_mbcnt_lo_u32_b32 %0, -1, 0\n\tv_mbcnt_hi_u32_b32 %0, -1, %0" : "=v"(l)); return l; }
; __device__ __forceinline__ unsigned xb_ld(unsigned* p)              { return __hip_atomic_load(p, __ATOMIC_RELAXED, __HIP_MEMORY_SCOPE_AGENT); }
; #define XB_SPIN(cond, bar) do { unsigned _sp = 0; while (cond) { __builtin_amdgcn_s_sleep(1); \
;     if ((++_sp & 255u) == 0u) { if (xb_ld(&(bar)[XB_TMO])) break; if (_sp > XB_SPIN_CAP) { atomicAdd(&(bar)[XB_TMO], 1u); break; } } } } while (0)
; __device__ __forceinline__ void xcd_barrier(const XcdBarrier& b, const int WID) {
;     ...
;         } else {
;             XB_SPIN(xb_ld(&bar[XB_XGEN(b.x)]) == gen, bar);
;             __builtin_amdgcn_fence(__ATOMIC_ACQUIRE, "agent");
;             asm volatile("s_waitcnt vmcnt(0)" ::: "memory");
;         }
;     }
;     __syncthreads();
; __global__ void __launch_bounds__(512) mega(Params p) {
;     ...
;     grid.sync();
;     if (WID == 0 && lane_id_() == 0) { bool uni = (G == 256);
;         for (int j = 0; j < 16; ++j) { const unsigned cnt = xb_ld(&xb.bar[XB_XCNT(j)]); uni = uni && (cnt == (j < 8 ? 32u : 0u)); }
;         stw[3] = uni ? 1u : 0u; }
;     __syncthreads();
;     const bool uni_ = __builtin_amdgcn_readfirstlane((int)stw[3]) != 0; const int rank_ = __builtin_amdgcn_readfirstlane((int)stw[2]);
.Lgb_xdone:
	buffer_inv sc1
	s_waitcnt vmcnt(0)
.Lgb_done:
	s_waitcnt lgkmcnt(0)
.LBB0_73:
	s_or_b64 exec, exec, s[0:1]
	s_cmp_lt_u32 s40, 64
	s_cselect_b64 s[82:83], -1, 0
	s_and_b64 vcc, exec, s[82:83]
	s_barrier
	s_cbranch_vccz .LBB0_77
	v_mbcnt_lo_u32_b32 v0, -1, 0
	v_mbcnt_hi_u32_b32 v0, -1, v0
	s_nop 0
	v_cmp_eq_u32_e32 vcc, 0, v0
	s_and_saveexec_b64 s[38:39], vcc
	s_cbranch_execz .LBB0_76
	v_mov_b32_e32 v0, 0x1de00000
	global_load_dword v1, v0, s[94:95] offset:1024 sc1
	global_load_dword v2, v0, s[94:95] offset:1280 sc1
	global_load_dword v3, v0, s[94:95] offset:1536 sc1
	global_load_dword v4, v0, s[94:95] offset:1792 sc1
	global_load_dword v5, v0, s[94:95] offset:2048 sc1
	global_load_dword v6, v0, s[94:95] offset:2304 sc1
	global_load_dword v7, v0, s[94:95] offset:2560 sc1
	global_load_dword v8, v0, s[94:95] offset:2816 sc1
	global_load_dword v9, v0, s[94:95] offset:3072 sc1
	global_load_dword v10, v0, s[94:95] offset:3328 sc1
	global_load_dword v11, v0, s[94:95] offset:3584 sc1
	global_load_dword v12, v0, s[94:95] offset:3840 sc1
	v_mov_b32_e32 v0, 0x1de01000
	global_load_dword v13, v0, s[94:95] sc1
	global_load_dword v14, v0, s[94:95] offset:256 sc1
	global_load_dword v15, v0, s[94:95] offset:512 sc1
	global_load_dword v16, v0, s[94:95] offset:768 sc1
	s_cmpk_eq_i32 s96, 0x100
	s_cselect_b64 s[34:35], -1, 0
	s_add_i32 s33, 0, 0x253fc
	s_waitcnt vmcnt(15)
	v_cmp_eq_u32_e32 vcc, 32, v1
	s_waitcnt vmcnt(14)
	v_cmp_eq_u32_e64 s[0:1], 32, v2
	s_and_b64 s[34:35], s[34:35], vcc
	s_waitcnt vmcnt(13)
	v_cmp_eq_u32_e64 s[4:5], 32, v3
	s_and_b64 s[0:1], s[34:35], s[0:1]
	s_waitcnt vmcnt(12)
	v_cmp_eq_u32_e64 s[6:7], 32, v4
	s_and_b64 s[0:1], s[0:1], s[4:5]
	s_waitcnt vmcnt(11)
	v_cmp_eq_u32_e64 s[8:9], 32, v5
	s_and_b64 s[0:1], s[0:1], s[6:7]
	s_waitcnt vmcnt(10)
	v_cmp_eq_u32_e64 s[10:11], 32, v6
	s_and_b64 s[0:1], s[0:1], s[8:9]
	s_waitcnt vmcnt(9)
	v_cmp_eq_u32_e64 s[12:13], 32, v7
	s_and_b64 s[0:1], s[0:1], s[10:11]
	s_waitcnt vmcnt(8)
	v_cmp_eq_u32_e64 s[14:15], 32, v8
	s_and_b64 s[0:1], s[0:1], s[12:13]
	s_waitcnt vmcnt(7)
	v_cmp_eq_u32_e64 s[16:17], 0, v9
	s_and_b64 s[0:1], s[0:1], s[14:15]
	s_waitcnt vmcnt(6)
	v_cmp_eq_u32_e64 s[18:19], 0, v10
	s_and_b64 s[0:1], s[0:1], s[16:17]
	s_waitcnt vmcnt(5)
	v_cmp_eq_u32_e64 s[20:21], 0, v11
	s_and_b64 s[0:1], s[0:1], s[18:19]
	s_waitcnt vmcnt(4)
	v_cmp_eq_u32_e64 s[22:23], 0, v12
	s_and_b64 s[0:1], s[0:1], s[20:21]
	s_waitcnt vmcnt(3)
	v_cmp_eq_u32_e64 s[24:25], 0, v13
	s_and_b64 s[0:1], s[0:1], s[22:23]
	s_waitcnt vmcnt(2)
	v_cmp_eq_u32_e64 s[26:27], 0, v14
	s_and_b64 s[0:1], s[0:1], s[24:25]
	s_waitcnt vmcnt(1)
	v_cmp_eq_u32_e64 s[28:29], 0, v15
	s_and_b64 s[0:1], s[0:1], s[26:27]
	s_waitcnt vmcnt(0)
	v_cmp_eq_u32_e64 s[30:31], 0, v16
	s_and_b64 s[0:1], s[0:1], s[28:29]
	s_and_b64 s[0:1], s[0:1], s[30:31]
	v_cndmask_b32_e64 v0, 0, 1, s[0:1]
	v_mov_b32_e32 v1, s33
	ds_write_b32 v1, v0

; __global__ void __launch_bounds__(512) mega(Params p) {
;     ...
;     { pg8::StaticOrder S; S.init(MTOK, DM, G, cg_); pg8::Unit u; int last = -1;
;       for (int i = 0; S.next(i, u); ++i) if (u.pm != last) { conv_fixup((const float*)(ws + WS_UEDGE), p.in[10], p.in[11], (bf16_t*)(ws + WS_ACT), u.pm, WID); last = u.pm; }
;       __threadfence(); __syncthreads();
;       pg8::Gemm g{(const bf16_t*)(ws + WS_ACT), (const bf16_t*)(ws + WS_WDOWN), MTOK, DM, FF};
;       pg8::EpiResid<true> E{(const void*)(ws + WS_H1B), (bf16_t*)(ws + WS_H1B), (float*)(ws + WS_SSQ2)}; pg8::gemm_phase(WID, lds, g, S, E); }
.LBB0_892:
	v_readlane_b32 s56, v254, 15
	v_readlane_b32 s58, v251, 33
	v_readlane_b32 s60, v254, 7
	s_and_b64 vcc, exec, s[38:39]
	v_readlane_b32 s57, v254, 16
	v_readlane_b32 s59, v251, 34
	v_readlane_b32 s61, v254, 8
	s_waitcnt vmcnt(0)
	s_barrier
	v_mbcnt_lo_u32_b32 v16, -1, 0
	v_mbcnt_hi_u32_b32 v16, -1, v16
	s_cbranch_vccnz .LBB0_898
	s_lshr_b32 s2, s72, 29
	s_add_i32 s8, s33, s2
	s_and_b32 s2, s8, -8
	s_sub_i32 s9, s33, s2
	s_cmp_gt_i32 s9, -1
	s_cbranch_scc0 .LBB0_895
	s_lshl_b32 s10, s9, 6
	s_cbranch_execz .LBB0_896
	s_branch .LBB0_897

; __global__ void __launch_bounds__(512) mega(Params p) {
	.amdhsa_kernel _Z4mega6Params
		.amdhsa_group_segment_fixed_size 0
		.amdhsa_private_segment_fixed_size 0
		.amdhsa_kernarg_size 408
		.amdhsa_user_sgpr_count 2
		.amdhsa_user_sgpr_dispatch_ptr 0
		.amdhsa_user_sgpr_queue_ptr 0
		.amdhsa_user_sgpr_kernarg_segment_ptr 1
		.amdhsa_user_sgpr_dispatch_id 0
		.amdhsa_user_sgpr_kernarg_preload_length 0
		.amdhsa_user_sgpr_kernarg_preload_offset 0
		.amdhsa_user_sgpr_private_segment_size 0
		.amdhsa_uses_dynamic_stack 0
		.amdhsa_enable_private_segment 0
		.amdhsa_system_sgpr_workgroup_id_x 1
		.amdhsa_system_sgpr_workgroup_id_y 0
		.amdhsa_system_sgpr_workgroup_id_z 0
		.amdhsa_system_sgpr_workgroup_info 0
		.amdhsa_system_vgpr_workitem_id 2
		.amdhsa_next_free_vgpr 255
		.amdhsa_next_free_sgpr 102
		.amdhsa_accum_offset 256
		.amdhsa_reserve_vcc 1
		.amdhsa_float_round_mode_32 0
		.amdhsa_float_round_mode_16_64 0
		.amdhsa_float_denorm_mode_32 3
		.amdhsa_float_denorm_mode_16_64 3
		.amdhsa_dx10_clamp 1
		.amdhsa_ieee_mode 1
		.amdhsa_fp16_overflow 0
		.amdhsa_tg_split 0
		.amdhsa_exception_fp_ieee_invalid_op 0
		.amdhsa_exception_fp_denorm_src 0
		.amdhsa_exception_fp_ieee_div_zero 0
		.amdhsa_exception_fp_ieee_overflow 0
		.amdhsa_exception_fp_ieee_underflow 0
		.amdhsa_exception_fp_ieee_inexact 0
		.amdhsa_exception_int_div_zero 0
	.end_amdhsa_kernel
